# m3 + strategy 4: one static s_setprio 1 for waves 4-7 across the index unit loop and the attention unit loop (reset to 0 at their exits)
# speedup vs baseline: 1.0007x; 1.0007x over previous
.LBB0_1276:
	v_readlane_b32 s0, v253, 16
	v_readlane_b32 s1, v253, 17
	s_andn2_b64 vcc, exec, s[0:1]
	s_cbranch_vccnz .LBB0_2885
	v_readlane_b32 s0, v252, 26
	v_readlane_b32 s1, v252, 27
	s_lshl_b64 s[0:1], s[0:1], 1
	s_add_u32 s0, s6, s0
	s_addc_u32 s1, s7, s1
	s_add_u32 s0, s0, 0x9400000
	s_addc_u32 s1, s1, 0
	v_writelane_b32 v251, s0, 44
	s_nop 1
	v_writelane_b32 v251, s1, 45
	s_add_u32 s0, s6, 0xa600000
	s_addc_u32 s1, s7, 0
	v_writelane_b32 v251, s0, 46
	s_nop 1
	v_writelane_b32 v251, s1, 47
	s_add_u32 s0, s6, 0xa400000
	s_addc_u32 s1, s7, 0
	v_writelane_b32 v251, s0, 48
	s_nop 1
	v_writelane_b32 v251, s1, 49
	s_add_u32 s0, s6, 0x4400000
	s_addc_u32 s1, s7, 0
	v_writelane_b32 v251, s0, 50
	s_mov_b32 s6, 0
	s_nop 0
	v_writelane_b32 v251, s1, 51
	v_readfirstlane_b32 s0, v0
	s_cmpk_lt_u32 s0, 0x100
	s_cbranch_scc1 .Lprio_i
	s_setprio 1
.Lprio_i:
	s_branch .LBB0_1279
.LBB0_1278:
	v_add_u32_e32 v11, 0x20000, v38
	v_mov_b32_e32 v6, v189
	s_waitcnt lgkmcnt(0)
	s_barrier
	v_ashrrev_i32_e32 v10, 5, v37
	ds_read_b128 v[2:5], v11
	s_or_b32 s68, s24, s92
	v_mov_b32_e32 v7, v6
	v_mov_b32_e32 v8, v6
	v_mov_b32_e32 v9, v6
	ds_write_b128 v11, v[6:9]
	v_ashrrev_i32_e32 v11, 31, v10
	v_lshl_add_u64 v[6:7], v[10:11], 0, s[68:69]
	v_readlane_b32 s0, v251, 50
	v_lshlrev_b64 v[6:7], 9, v[6:7]
	v_readlane_b32 s1, v251, 51
	v_and_b32_e32 v188, 0x1f0, v39
	s_add_i32 s6, s6, 1
	v_lshl_add_u64 v[6:7], s[0:1], 0, v[6:7]
	v_lshl_add_u64 v[6:7], v[6:7], 0, v[188:189]
	s_cmp_lg_u32 s6, 4
	s_waitcnt lgkmcnt(1)
	global_store_dwordx4 v[6:7], v[2:5], off
	s_cbranch_scc0 .LBB0_2884

.LBB0_2884:
	s_setprio 0
	v_readlane_b32 s61, v251, 36

.LBB0_2967:
	v_readfirstlane_b32 s0, v0
	s_cmpk_lt_u32 s0, 0x100
	s_cbranch_scc1 .Lprio_a
	s_setprio 1

.LBB0_3019:
	s_setprio 0
	v_readlane_b32 s0, v251, 26
	s_nop 1
	v_mov_b32_e32 v2, s0
	ds_read_b32 v2, v2
	s_waitcnt lgkmcnt(0)
	v_readfirstlane_b32 s0, v2
	s_cmp_eq_u32 s0, 0
	s_cbranch_scc1 .LBB0_3031
	s_waitcnt vmcnt(0)
	s_waitcnt vmcnt(0)
	s_barrier
	s_mov_b64 s[0:1], exec
	v_readlane_b32 s6, v253, 6
	v_readlane_b32 s7, v253, 7
	s_and_b64 s[6:7], s[0:1], s[6:7]
	s_mov_b64 exec, s[6:7]
	s_cbranch_execz .LBB0_3037
	v_readlane_b32 s8, v253, 4
	v_readlane_b32 s6, v251, 27
	v_readlane_b32 s9, v253, 5
	s_waitcnt vmcnt(0) expcnt(0) lgkmcnt(0)
	v_mov_b32_e32 v2, s6
	ds_read_b32 v2, v2
	v_readlane_b32 s6, v253, 59
	s_lshl_b32 s6, s6, 2
	s_add_u32 s6, s8, s6
	s_addc_u32 s7, s9, 0
	s_waitcnt lgkmcnt(0)
	v_max_u32_e32 v5, 1, v2
	v_mov_b32_e32 v2, s6
	v_add_co_u32_e32 v2, vcc, 0x3000, v2
	v_mov_b32_e32 v3, s7
	s_nop 0
	v_addc_co_u32_e32 v3, vcc, 0, v3, vcc
	flat_atomic_add v2, v[2:3], v186 offset:1536 sc0
	v_cvt_f32_u32_e32 v3, v5
	v_sub_u32_e32 v4, 0, v5
	s_add_u32 s6, s6, 0x4600
	s_addc_u32 s7, s7, 0
	v_rcp_iflag_f32_e32 v3, v3
	s_mov_b64 s[12:13], -1
	v_mul_f32_e32 v3, 0x4f7ffffe, v3
	v_cvt_u32_f32_e32 v3, v3
	v_mul_lo_u32 v4, v4, v3
	v_mul_hi_u32 v4, v3, v4
	v_add_u32_e32 v3, v3, v4
	s_waitcnt vmcnt(0) lgkmcnt(0)
	v_mul_hi_u32 v3, v2, v3
	v_mul_lo_u32 v4, v3, v5
	v_sub_u32_e32 v4, v2, v4
	v_cmp_ge_u32_e32 vcc, v4, v5
	v_add_u32_e32 v6, 1, v3
	v_add_u32_e32 v2, 1, v2
	v_cndmask_b32_e32 v3, v3, v6, vcc
	v_sub_u32_e32 v6, v4, v5
	v_cndmask_b32_e32 v4, v4, v6, vcc
	v_cmp_ge_u32_e32 vcc, v4, v5
	v_add_u32_e32 v4, 1, v3
	s_nop 0
	v_cndmask_b32_e32 v4, v3, v4, vcc
	v_mul_lo_u32 v3, v5, v4
	v_add_u32_e32 v3, v3, v5
	v_cmp_ne_u32_e32 vcc, v2, v3
	v_mov_b64_e32 v[2:3], s[6:7]
	s_and_saveexec_b64 s[10:11], vcc
	s_cbranch_execz .LBB0_3034
	v_mov_b64_e32 v[2:3], s[6:7]
	flat_load_dword v2, v[2:3] sc1
	s_mov_b64 s[16:17], 0
	s_waitcnt vmcnt(0) lgkmcnt(0)
	v_cmp_eq_u32_e32 vcc, v2, v4
	s_and_saveexec_b64 s[14:15], vcc
	s_cbranch_execz .LBB0_3033
	s_add_u32 s12, s8, 0x200
	s_addc_u32 s13, s9, 0
	s_mov_b32 s34, 1
	s_mov_b64 s[8:9], 0
	s_branch .LBB0_3025
